# scan: register-staged operands with the LDS writes issued right after each half-phase's LDS reads (draining under the MFMA chains)
# baseline (speedup 1.0000x reference)
.Lscan_loop:
	s_and_b32 s7, s6, 3
	s_lshl_b32 s7, s7, 12
	v_add_u32_e32 v23, s7, v22
	ds_read_b128 v[32:35], v10 offset:0
	ds_read_b128 v[48:51], v11 offset:0
	ds_read_b128 v[36:39], v10 offset:64
	ds_read_b128 v[52:55], v12 offset:0
	ds_read_b128 v[40:43], v10 offset:128
	ds_read_b128 v[56:59], v13 offset:0
	ds_read_b128 v[44:47], v10 offset:192
	ds_read_b128 v[60:63], v14 offset:0
	ds_read_u16 v80, v23 offset:0
	ds_read_u16 v81, v23 offset:64
	ds_read_u16 v82, v23 offset:128
	ds_read_u16 v83, v23 offset:192
	s_add_u32 s33, s6, 1
	s_min_u32 s33, s33, 31
	s_add_u32 s36, s6, 2
	s_min_u32 s36, s36, 31
	s_waitcnt vmcnt(5)
	ds_write_b128 v179, v[136:139] offset:0
	ds_write_b128 v179, v[140:143] offset:1024
	ds_write_b128 v180, v[144:147] offset:0
	s_add_u32 s8, s6, 1
	s_and_b32 s8, s8, 3
	s_lshl_b32 s8, s8, 12
	v_add_u32_e32 v182, s8, v181
	ds_write_b128 v182, v[148:151]
	s_lshl_b32 s7, s33, 14
	s_add_u32 s26, s14, s7
	s_addc_u32 s27, s15, 0
	global_load_dwordx4 v[136:139], v5, s[26:27]
	global_load_dwordx4 v[140:143], v6, s[26:27]
	s_lshl_b32 s7, s33, 13
	s_add_u32 s28, s18, s7
	s_addc_u32 s29, s19, 0
	global_load_dwordx4 v[144:147], v7, s[28:29]
	s_lshl_b32 s7, s36, 14
	s_add_u32 s26, s24, s7
	s_addc_u32 s27, s25, 0
	global_load_dwordx4 v[148:151], v8, s[26:27]
	v_readlane_b32 s37, v24, s6
	s_nop 1
	v_mul_f32_e32 v92, s37, v92
	v_mul_f32_e32 v93, s37, v93
	v_mul_f32_e32 v94, s37, v94
	v_mul_f32_e32 v95, s37, v95
	v_mul_f32_e32 v96, s37, v96
	v_mul_f32_e32 v97, s37, v97
	v_mul_f32_e32 v98, s37, v98
	v_mul_f32_e32 v99, s37, v99
	s_waitcnt lgkmcnt(14)
	v_mfma_f32_16x16x32_bf16 v[84:87], v[48:51], v[32:35], 0
	s_waitcnt lgkmcnt(12)
	v_mfma_f32_16x16x32_bf16 v[84:87], v[52:55], v[36:39], v[84:87]
	s_waitcnt lgkmcnt(10)
	v_mfma_f32_16x16x32_bf16 v[84:87], v[56:59], v[40:43], v[84:87]
	s_waitcnt lgkmcnt(8)
	v_mfma_f32_16x16x32_bf16 v[84:87], v[60:63], v[44:47], v[84:87]
	ds_read_b128 v[64:67], v11 offset:32768
	ds_read_b128 v[68:71], v12 offset:32768
	ds_read_b128 v[72:75], v13 offset:32768
	ds_read_b128 v[76:79], v14 offset:32768
	s_waitcnt lgkmcnt(4)
	v_lshlrev_b32_e32 v80, 16, v80
	v_lshlrev_b32_e32 v81, 16, v81
	v_lshlrev_b32_e32 v82, 16, v82
	v_lshlrev_b32_e32 v83, 16, v83
	v_sub_f32_e32 v26, v80, v84
	v_sub_f32_e32 v27, v81, v85
	v_sub_f32_e32 v28, v82, v86
	v_sub_f32_e32 v29, v83, v87
	v_cvt_pk_bf16_f32 v26, v26, v27
	v_cvt_pk_bf16_f32 v27, v28, v29
	ds_write_b64 v20, v[26:27]
	s_waitcnt lgkmcnt(0)
	s_barrier
	ds_read_b128 v[100:103], v19
	ds_read_b128 v[108:111], v15 offset:0
	ds_read_b128 v[112:115], v15 offset:2048
	ds_read_b128 v[104:107], v19 offset:64
	ds_read_b128 v[116:119], v16 offset:0
	ds_read_b128 v[120:123], v16 offset:2048
	ds_read_b128 v[124:127], v17 offset:0
	ds_read_b128 v[128:131], v18 offset:0
	s_waitcnt vmcnt(5)
	ds_write_b128 v178, v[162:165] offset:16384
	ds_write_b128 v178, v[166:169] offset:17408
	ds_write_b128 v178, v[170:173] offset:49152
	ds_write_b128 v178, v[174:177] offset:50176
	s_lshl_b32 s7, s36, 14
	s_add_u32 s26, s10, s7
	s_addc_u32 s27, s11, 0
	global_load_dwordx4 v[162:165], v3, s[26:27]
	global_load_dwordx4 v[166:169], v4, s[26:27]
	s_lshl_b32 s7, s36, 14
	s_add_u32 s26, s12, s7
	s_addc_u32 s27, s13, 0
	global_load_dwordx4 v[170:173], v3, s[26:27]
	global_load_dwordx4 v[174:177], v4, s[26:27]
	v_mfma_f32_16x16x32_bf16 v[88:91], v[32:35], v[64:67], 0
	v_mfma_f32_16x16x32_bf16 v[88:91], v[36:39], v[68:71], v[88:91]
	v_mfma_f32_16x16x32_bf16 v[88:91], v[40:43], v[72:75], v[88:91]
	v_mfma_f32_16x16x32_bf16 v[88:91], v[44:47], v[76:79], v[88:91]
	s_waitcnt lgkmcnt(10)
	v_mfma_f32_16x16x32_bf16 v[92:95], v[108:111], v[100:103], v[92:95]
	s_waitcnt lgkmcnt(9)
	v_mfma_f32_16x16x32_bf16 v[96:99], v[112:115], v[100:103], v[96:99]
	s_waitcnt lgkmcnt(7)
	v_mfma_f32_16x16x32_bf16 v[92:95], v[116:119], v[104:107], v[92:95]
	s_waitcnt lgkmcnt(6)
	v_mfma_f32_16x16x32_bf16 v[96:99], v[120:123], v[104:107], v[96:99]
	s_waitcnt lgkmcnt(5)
	v_mfma_f32_16x16x32_bf16 v[88:91], v[100:103], v[124:127], v[88:91]
	s_waitcnt lgkmcnt(4)
	v_mfma_f32_16x16x32_bf16 v[88:91], v[104:107], v[128:131], v[88:91]
	s_lshl_b32 s7, s6, 14
	s_add_u32 s28, s24, s7
	s_addc_u32 s29, s25, 0
	s_nop 1
	v_cvt_pk_bf16_f32 v26, v92, v93
	v_cvt_pk_bf16_f32 v27, v94, v95
	v_cvt_pk_bf16_f32 v28, v96, v97
	v_cvt_pk_bf16_f32 v29, v98, v99
	ds_write_b64 v21, v[26:27]
	ds_write_b64 v21, v[28:29] offset:32
	v_cvt_pk_bf16_f32 v80, v88, v89
	v_cvt_pk_bf16_f32 v81, v90, v91
	global_store_dwordx2 v9, v[80:81], s[28:29]
	s_add_u32 s6, s6, 1
	s_waitcnt lgkmcnt(0)
	s_barrier
	s_and_b32 s7, s6, 3
	s_lshl_b32 s7, s7, 12
	v_add_u32_e32 v23, s7, v22
	ds_read_b128 v[32:35], v10 offset:0
	ds_read_b128 v[48:51], v11 offset:16384
	ds_read_b128 v[36:39], v10 offset:64
	ds_read_b128 v[52:55], v12 offset:16384
	ds_read_b128 v[40:43], v10 offset:128
	ds_read_b128 v[56:59], v13 offset:16384
	ds_read_b128 v[44:47], v10 offset:192
	ds_read_b128 v[60:63], v14 offset:16384
	ds_read_u16 v80, v23 offset:0
	ds_read_u16 v81, v23 offset:64
	ds_read_u16 v82, v23 offset:128
	ds_read_u16 v83, v23 offset:192
	s_add_u32 s33, s6, 1
	s_min_u32 s33, s33, 31
	s_add_u32 s36, s6, 2
	s_min_u32 s36, s36, 31
	s_waitcnt vmcnt(5)
	ds_write_b128 v179, v[136:139] offset:16384
	ds_write_b128 v179, v[140:143] offset:17408
	ds_write_b128 v180, v[144:147] offset:8192
	s_add_u32 s8, s6, 1
	s_and_b32 s8, s8, 3
	s_lshl_b32 s8, s8, 12
	v_add_u32_e32 v182, s8, v181
	ds_write_b128 v182, v[148:151]
	s_lshl_b32 s7, s33, 14
	s_add_u32 s26, s14, s7
	s_addc_u32 s27, s15, 0
	global_load_dwordx4 v[136:139], v5, s[26:27]
	global_load_dwordx4 v[140:143], v6, s[26:27]
	s_lshl_b32 s7, s33, 13
	s_add_u32 s28, s18, s7
	s_addc_u32 s29, s19, 0
	global_load_dwordx4 v[144:147], v7, s[28:29]
	s_lshl_b32 s7, s36, 14
	s_add_u32 s26, s24, s7
	s_addc_u32 s27, s25, 0
	global_load_dwordx4 v[148:151], v8, s[26:27]
	v_readlane_b32 s37, v24, s6
	s_nop 1
	v_mul_f32_e32 v92, s37, v92
	v_mul_f32_e32 v93, s37, v93
	v_mul_f32_e32 v94, s37, v94
	v_mul_f32_e32 v95, s37, v95
	v_mul_f32_e32 v96, s37, v96
	v_mul_f32_e32 v97, s37, v97
	v_mul_f32_e32 v98, s37, v98
	v_mul_f32_e32 v99, s37, v99
	s_waitcnt lgkmcnt(14)
	v_mfma_f32_16x16x32_bf16 v[84:87], v[48:51], v[32:35], 0
	s_waitcnt lgkmcnt(12)
	v_mfma_f32_16x16x32_bf16 v[84:87], v[52:55], v[36:39], v[84:87]
	s_waitcnt lgkmcnt(10)
	v_mfma_f32_16x16x32_bf16 v[84:87], v[56:59], v[40:43], v[84:87]
	s_waitcnt lgkmcnt(8)
	v_mfma_f32_16x16x32_bf16 v[84:87], v[60:63], v[44:47], v[84:87]
	ds_read_b128 v[64:67], v11 offset:49152
	ds_read_b128 v[68:71], v12 offset:49152
	ds_read_b128 v[72:75], v13 offset:49152
	ds_read_b128 v[76:79], v14 offset:49152
	s_waitcnt lgkmcnt(4)
	v_lshlrev_b32_e32 v80, 16, v80
	v_lshlrev_b32_e32 v81, 16, v81
	v_lshlrev_b32_e32 v82, 16, v82
	v_lshlrev_b32_e32 v83, 16, v83
	v_sub_f32_e32 v26, v80, v84
	v_sub_f32_e32 v27, v81, v85
	v_sub_f32_e32 v28, v82, v86
	v_sub_f32_e32 v29, v83, v87
	v_cvt_pk_bf16_f32 v26, v26, v27
	v_cvt_pk_bf16_f32 v27, v28, v29
	ds_write_b64 v20, v[26:27]
	s_waitcnt lgkmcnt(0)
	s_barrier
	ds_read_b128 v[100:103], v19
	ds_read_b128 v[108:111], v15 offset:16384
	ds_read_b128 v[112:115], v15 offset:18432
	ds_read_b128 v[104:107], v19 offset:64
	ds_read_b128 v[116:119], v16 offset:16384
	ds_read_b128 v[120:123], v16 offset:18432
	ds_read_b128 v[124:127], v17 offset:8192
	ds_read_b128 v[128:131], v18 offset:8192
	s_waitcnt vmcnt(5)
	ds_write_b128 v178, v[162:165] offset:0
	ds_write_b128 v178, v[166:169] offset:1024
	ds_write_b128 v178, v[170:173] offset:32768
	ds_write_b128 v178, v[174:177] offset:33792
	s_lshl_b32 s7, s36, 14
	s_add_u32 s26, s10, s7
	s_addc_u32 s27, s11, 0
	global_load_dwordx4 v[162:165], v3, s[26:27]
	global_load_dwordx4 v[166:169], v4, s[26:27]
	s_lshl_b32 s7, s36, 14
	s_add_u32 s26, s12, s7
	s_addc_u32 s27, s13, 0
	global_load_dwordx4 v[170:173], v3, s[26:27]
	global_load_dwordx4 v[174:177], v4, s[26:27]
	v_mfma_f32_16x16x32_bf16 v[88:91], v[32:35], v[64:67], 0
	v_mfma_f32_16x16x32_bf16 v[88:91], v[36:39], v[68:71], v[88:91]
	v_mfma_f32_16x16x32_bf16 v[88:91], v[40:43], v[72:75], v[88:91]
	v_mfma_f32_16x16x32_bf16 v[88:91], v[44:47], v[76:79], v[88:91]
	s_waitcnt lgkmcnt(10)
	v_mfma_f32_16x16x32_bf16 v[92:95], v[108:111], v[100:103], v[92:95]
	s_waitcnt lgkmcnt(9)
	v_mfma_f32_16x16x32_bf16 v[96:99], v[112:115], v[100:103], v[96:99]
	s_waitcnt lgkmcnt(7)
	v_mfma_f32_16x16x32_bf16 v[92:95], v[116:119], v[104:107], v[92:95]
	s_waitcnt lgkmcnt(6)
	v_mfma_f32_16x16x32_bf16 v[96:99], v[120:123], v[104:107], v[96:99]
	s_waitcnt lgkmcnt(5)
	v_mfma_f32_16x16x32_bf16 v[88:91], v[100:103], v[124:127], v[88:91]
	s_waitcnt lgkmcnt(4)
	v_mfma_f32_16x16x32_bf16 v[88:91], v[104:107], v[128:131], v[88:91]
	s_lshl_b32 s7, s6, 14
	s_add_u32 s28, s24, s7
	s_addc_u32 s29, s25, 0
	s_nop 1
	v_cvt_pk_bf16_f32 v26, v92, v93
	v_cvt_pk_bf16_f32 v27, v94, v95
	v_cvt_pk_bf16_f32 v28, v96, v97
	v_cvt_pk_bf16_f32 v29, v98, v99
	ds_write_b64 v21, v[26:27]
	ds_write_b64 v21, v[28:29] offset:32
	v_cvt_pk_bf16_f32 v80, v88, v89
	v_cvt_pk_bf16_f32 v81, v90, v91
	global_store_dwordx2 v9, v[80:81], s[28:29]
	s_add_u32 s6, s6, 1
	s_waitcnt lgkmcnt(0)
	s_barrier
	s_cmp_lt_u32 s6, 32
	s_cbranch_scc1 .Lscan_loop
	s_lshl_b32 s56, s77, 5
	s_and_b32 s57, s40, 3
	s_lshl_b32 s72, s40, 5
	s_waitcnt vmcnt(0)
	v_readfirstlane_b32 s3, v194
	s_cmp_gt_u32 s3, 63
	s_barrier
	s_cbranch_scc1 .LBB0_421
	s_waitcnt vmcnt(2)
	v_mbcnt_lo_u32_b32 v0, -1, 0
	v_mbcnt_hi_u32_b32 v0, -1, v0
	s_nop 0
	v_cmp_eq_u32_e32 vcc, 0, v0
	s_and_saveexec_b64 s[6:7], vcc
	s_cbranch_execz .LBB0_420
	s_add_i32 s3, 0, 0x23ff0
	v_mov_b32_e32 v0, s3
	s_waitcnt vmcnt(0) expcnt(0) lgkmcnt(0)
	ds_read_b32 v2, v0
	s_add_i32 s3, 0, 0x23ff4
	v_mov_b32_e32 v0, s3
	ds_read_b32 v0, v0
	s_waitcnt lgkmcnt(1)
	v_cmp_ne_u32_e32 vcc, 0, v2
	s_cbranch_vccnz .LBB0_384
	s_mov_b32 s3, 1
	v_mov_b32_e32 v16, 0
	s_branch .LBB0_372
